# M3 mix_out GLA path: Q/K/V tile loads batched; M3 inter phase: 8 state fragments loaded together (on top of kv_local GLA batching)
# baseline (speedup 1.0000x reference)
.LBB0_885:
	s_waitcnt lgkmcnt(0)
	s_add_u32 s82, s34, 0xf795400
	v_ashrrev_i32_e32 v137, 5, v136
	v_and_b32_e32 v129, 31, v136
	s_addc_u32 s83, s35, 0
	s_and_b32 s7, s4, 3
	s_and_b32 s6, s2, 7
	s_ashr_i32 s5, s2, 3
	v_cvt_f32_ubyte0_e32 v0, s7
	s_lshl_b32 s8, s6, 11
	s_lshl_b32 s56, s5, 6
	v_sub_f32_e32 v8, 0xc0a00000, v0
	s_add_i32 s57, s56, s8
	v_cmp_gt_f32_e64 s[38:39], s90, v8
	s_and_b64 s[8:9], s[38:39], exec
	s_cselect_b32 s58, 0xffffffc0, 0
	s_cmp_gt_u32 s4, 3
	s_cselect_b64 s[22:23], -1, 0
	v_and_b32_e32 v77, 7, v136
	s_and_b64 vcc, exec, s[22:23]
	s_mul_hi_i32 s8, s57, 0x1e00
	s_mul_i32 s9, s57, 0x1e00
	v_lshlrev_b32_e32 v192, 4, v77
	v_ashrrev_i32_e32 v113, 3, v136
	s_cbranch_vccz .LBB0_935
	s_add_u32 s10, s34, s9
	s_addc_u32 s11, s35, s8
	s_lshl_b32 s12, s7, 7
	s_add_u32 s10, s10, s12
	s_addc_u32 s11, s11, 0
	v_ashrrev_i32_e32 v140, 3, v136
	v_lshl_add_u64 v[6:7], s[10:11], 0, v[192:193]
	v_cmp_gt_i32_e32 vcc, 64, v140
	v_lshl_add_u32 v23, v77, 4, s33
	v_mul_lo_u32 v1, v140, s85
	v_add_u32_e32 v11, v23, v1
	v_add_u32_e32 v1, 64, v136
	v_ashrrev_i32_e32 v9, 3, v1
	v_cmp_gt_i32_e64 s[40:41], 64, v9
	v_mul_lo_u32 v4, v9, s85
	v_add_u32_e32 v13, v23, v4
	v_add_u32_e32 v1, 0x80, v136
	v_ashrrev_i32_e32 v10, 3, v1
	v_cmp_gt_i32_e64 s[42:43], 64, v10
	v_mul_lo_u32 v4, v10, s85
	v_add_u32_e32 v15, v23, v4
	v_add_u32_e32 v1, 0xc0, v136
	v_ashrrev_i32_e32 v12, 3, v1
	v_cmp_gt_i32_e64 s[44:45], 64, v12
	v_mul_lo_u32 v4, v12, s85
	v_add_u32_e32 v17, v23, v4
	v_add_u32_e32 v1, 0x100, v136
	v_ashrrev_i32_e32 v14, 3, v1
	v_cmp_gt_i32_e64 s[46:47], 64, v14
	v_mul_lo_u32 v4, v14, s85
	v_add_u32_e32 v19, v23, v4
	v_add_u32_e32 v1, 0x140, v136
	v_ashrrev_i32_e32 v16, 3, v1
	v_cmp_gt_i32_e64 s[48:49], 64, v16
	v_mul_lo_u32 v4, v16, s85
	v_add_u32_e32 v21, v23, v4
	v_add_u32_e32 v1, 0x180, v136
	v_ashrrev_i32_e32 v18, 3, v1
	v_cmp_gt_i32_e64 s[50:51], 64, v18
	v_mul_lo_u32 v4, v18, s85
	v_add_u32_e32 v22, v23, v4
	v_add_u32_e32 v1, 0x1c0, v136
	v_ashrrev_i32_e32 v20, 3, v1
	v_cmp_gt_i32_e64 s[52:53], 64, v20
	v_mul_lo_u32 v4, v20, s85
	v_add_u32_e32 v23, v23, v4
	v_mad_i64_i32 v[2:3], s[10:11], v140, s84, v[6:7]
	global_load_dwordx4 v[24:27], v[2:3], off offset:2048
	global_load_dwordx4 v[56:59], v[2:3], off offset:2560
	global_load_dwordx4 v[180:183], v[2:3], off offset:3072
	v_mad_i64_i32 v[2:3], s[10:11], v9, s84, v[6:7]
	global_load_dwordx4 v[28:31], v[2:3], off offset:2048
	global_load_dwordx4 v[60:63], v[2:3], off offset:2560
	global_load_dwordx4 v[184:187], v[2:3], off offset:3072
	v_mad_i64_i32 v[2:3], s[10:11], v10, s84, v[6:7]
	global_load_dwordx4 v[32:35], v[2:3], off offset:2048
	global_load_dwordx4 v[156:159], v[2:3], off offset:2560
	global_load_dwordx4 v[188:191], v[2:3], off offset:3072
	v_mad_i64_i32 v[2:3], s[10:11], v12, s84, v[6:7]
	global_load_dwordx4 v[36:39], v[2:3], off offset:2048
	global_load_dwordx4 v[160:163], v[2:3], off offset:2560
	global_load_dwordx4 v[206:209], v[2:3], off offset:3072
	v_mad_i64_i32 v[2:3], s[10:11], v14, s84, v[6:7]
	global_load_dwordx4 v[40:43], v[2:3], off offset:2048
	global_load_dwordx4 v[164:167], v[2:3], off offset:2560
	global_load_dwordx4 v[210:213], v[2:3], off offset:3072
	v_mad_i64_i32 v[2:3], s[10:11], v16, s84, v[6:7]
	global_load_dwordx4 v[44:47], v[2:3], off offset:2048
	global_load_dwordx4 v[168:171], v[2:3], off offset:2560
	global_load_dwordx4 v[214:217], v[2:3], off offset:3072
	v_mad_i64_i32 v[2:3], s[10:11], v18, s84, v[6:7]
	global_load_dwordx4 v[48:51], v[2:3], off offset:2048
	global_load_dwordx4 v[172:175], v[2:3], off offset:2560
	global_load_dwordx4 v[218:221], v[2:3], off offset:3072
	v_mad_i64_i32 v[2:3], s[10:11], v20, s84, v[6:7]
	global_load_dwordx4 v[52:55], v[2:3], off offset:2048
	global_load_dwordx4 v[176:179], v[2:3], off offset:2560
	global_load_dwordx4 v[222:225], v[2:3], off offset:3072
	s_waitcnt vmcnt(23)
	ds_write_b128 v11, v[24:27]
	s_waitcnt vmcnt(22)
	ds_write_b128 v11, v[56:59] offset:9216
	s_waitcnt vmcnt(20)
	ds_write_b128 v13, v[28:31]
	s_waitcnt vmcnt(19)
	ds_write_b128 v13, v[60:63] offset:9216
	s_waitcnt vmcnt(17)
	ds_write_b128 v15, v[32:35]
	s_waitcnt vmcnt(16)
	ds_write_b128 v15, v[156:159] offset:9216
	s_waitcnt vmcnt(14)
	ds_write_b128 v17, v[36:39]
	s_waitcnt vmcnt(13)
	ds_write_b128 v17, v[160:163] offset:9216
	s_waitcnt vmcnt(11)
	ds_write_b128 v19, v[40:43]
	s_waitcnt vmcnt(10)
	ds_write_b128 v19, v[164:167] offset:9216
	s_waitcnt vmcnt(8)
	ds_write_b128 v21, v[44:47]
	s_waitcnt vmcnt(7)
	ds_write_b128 v21, v[168:171] offset:9216
	s_waitcnt vmcnt(5)
	ds_write_b128 v22, v[48:51]
	s_waitcnt vmcnt(4)
	ds_write_b128 v22, v[172:175] offset:9216
	s_waitcnt vmcnt(2)
	ds_write_b128 v23, v[52:55]
	s_waitcnt vmcnt(1)
	ds_write_b128 v23, v[176:179] offset:9216
	v_ashrrev_i32_e32 v0, 1, v136
	v_and_b32_e32 v68, -16, v0
	v_mul_u32_u24_e32 v0, 0x90, v129
	v_add3_u32 v0, s33, v68, v0
	ds_read_b128 v[64:67], v0
	ds_read_b128 v[88:91], v0 offset:32
	ds_read_b128 v[80:83], v0 offset:64
	ds_read_b128 v[84:87], v0 offset:96
	ds_read_b128 v[96:99], v0 offset:4608
	ds_read_b128 v[108:111], v0 offset:4640
	ds_read_b128 v[100:103], v0 offset:4672
	ds_read_b128 v[104:107], v0 offset:4704
	s_waitcnt lgkmcnt(0)
	s_waitcnt vmcnt(0)
	ds_write_b128 v11, v[180:183]
	ds_write_b128 v13, v[184:187]
	ds_write_b128 v15, v[188:191]
	ds_write_b128 v17, v[206:209]
	ds_write_b128 v19, v[210:213]
	ds_write_b128 v21, v[214:217]
	ds_write_b128 v22, v[218:221]
	ds_write_b128 v23, v[222:225]
	s_lshl_b32 s26, s7, 6
	v_lshlrev_b32_e32 v130, 3, v137
	v_ashrrev_i32_e32 v131, 31, v130
	v_or_b32_e32 v128, s57, v129
	v_or_b32_e32 v132, s56, v129
	v_add_u32_e32 v124, 1, v129
	s_mov_b64 s[40:41], 0
	v_mov_b32_e32 v138, s26
	s_branch .LBB0_936

.LBB0_954:
	s_ashr_i32 s4, s4, 2
	s_lshl_b32 s8, s4, 5
	s_lshl_b32 s6, s6, 2
	s_or_b32 s6, s8, s6
	s_or_b32 s6, s6, s7
	s_lshl_b32 s6, s6, 5
	s_add_i32 s6, s6, s5
	s_ashr_i32 s7, s6, 31
	s_lshl_b64 s[6:7], s[6:7], 13
	s_add_u32 s6, s34, s6
	s_addc_u32 s7, s35, s7
	v_lshlrev_b32_e32 v192, 7, v129
	v_lshl_add_u64 v[4:5], s[6:7], 0, v[192:193]
	v_lshlrev_b64 v[6:7], 1, v[130:131]
	v_lshl_add_u64 v[0:1], v[4:5], 0, v[6:7]
	s_mov_b64 s[6:7], 0xa280000
	s_mov_b32 s5, 0xa280000
	v_lshl_add_u64 v[8:9], v[0:1], 0, s[6:7]
	s_mov_b64 s[6:7], 0xa281000
	v_lshl_add_u64 v[72:73], v[4:5], 0, s[6:7]
	v_ashrrev_i32_e32 v71, 31, v130
	v_mov_b32_e32 v70, v130
	v_lshl_add_u64 v[74:75], v[70:71], 1, v[72:73]
	global_load_dwordx4 v[32:35], v[8:9], off
	global_load_dwordx4 v[36:39], v[8:9], off offset:32
	global_load_dwordx4 v[40:43], v[8:9], off offset:64
	global_load_dwordx4 v[44:47], v[8:9], off offset:96
	global_load_dwordx4 v[92:95], v[74:75], off
	global_load_dwordx4 v[112:115], v[74:75], off offset:32
	global_load_dwordx4 v[116:119], v[74:75], off offset:64
	global_load_dwordx4 v[120:123], v[74:75], off offset:96
	s_waitcnt lgkmcnt(0)
	s_waitcnt vmcnt(7)
	v_mfma_f32_32x32x16_bf16 v[48:63], v[32:35], v[64:67], 0
	v_mfma_f32_32x32x16_bf16 v[16:31], v[32:35], v[96:99], 0
	s_waitcnt vmcnt(6)
	v_mfma_f32_32x32x16_bf16 v[48:63], v[36:39], v[88:91], v[48:63]
	v_mfma_f32_32x32x16_bf16 v[16:31], v[36:39], v[108:111], v[16:31]
	s_waitcnt vmcnt(5)
	v_mfma_f32_32x32x16_bf16 v[48:63], v[40:43], v[80:83], v[48:63]
	v_mfma_f32_32x32x16_bf16 v[16:31], v[40:43], v[100:103], v[16:31]
	s_waitcnt vmcnt(4)
	v_mfma_f32_32x32x16_bf16 v[48:63], v[44:47], v[84:87], v[48:63]
	v_mfma_f32_32x32x16_bf16 v[16:31], v[44:47], v[104:107], v[16:31]
	s_waitcnt vmcnt(3)
	v_mfma_f32_32x32x16_bf16 v[32:47], v[92:95], v[64:67], 0
	v_mfma_f32_32x32x16_bf16 v[0:15], v[92:95], v[96:99], 0
	s_waitcnt vmcnt(2)
	v_mfma_f32_32x32x16_bf16 v[32:47], v[112:115], v[88:91], v[32:47]
	v_mfma_f32_32x32x16_bf16 v[0:15], v[112:115], v[108:111], v[0:15]
	s_waitcnt vmcnt(1)
	v_mfma_f32_32x32x16_bf16 v[32:47], v[116:119], v[80:83], v[32:47]
	v_mfma_f32_32x32x16_bf16 v[0:15], v[116:119], v[100:103], v[0:15]
	s_waitcnt vmcnt(0)
	v_mfma_f32_32x32x16_bf16 v[32:47], v[120:123], v[84:87], v[32:47]
	v_mfma_f32_32x32x16_bf16 v[0:15], v[120:123], v[104:107], v[0:15]
	v_add_u32_e32 v68, s33, v68
	v_cndmask_b32_e64 v69, 0, 1, s[22:23]
	s_mov_b64 s[40:41], -1
	v_cmp_ne_u32_e64 s[38:39], 1, v69
	s_andn2_b64 vcc, exec, s[22:23]
	v_mad_u32_u24 v141, v129, s85, v68
	s_cbranch_vccnz .LBB0_956
	ds_read_b128 v[92:95], v141 offset:9216
	ds_read_b128 v[120:123], v141 offset:9248
	ds_read_b128 v[112:115], v141 offset:9280
	ds_read_b128 v[116:119], v141 offset:9312
	s_mov_b64 s[40:41], 0
